# LN2: 16-byte loads (10 per token, one wait) with DPP pair unscramble instead of 20 8-byte loads in 4 serialized groups
# speedup vs baseline: 1.0010x; 1.0010x over previous
; __device__ __forceinline__ void run_phase(const Args& a, const int ph, LAS unsigned char* lds, const int tid, const int rpt) {
;     ...
;                 const bf16_t* x1r = (const bf16_t*)(ws + WS_X1B); const bf16_t* yb = (const bf16_t*)(ws + WS_YBUF); bf16_t* xb = (bf16_t*)(ws + WS_XB);
;                 const float* g2 = a.in[16] + l * 1024; const float* b2 = a.in[17] + l * 1024;
;                 f32x4 gv[4], bv[4];
; #pragma unroll
;                 for (int j = 0; j < 4; ++j) { gv[j] = *(const f32x4*)(g2 + 4 * (64 * j + lane)); bv[j] = *(const f32x4*)(b2 + 4 * (64 * j + lane)); }
;                 for (int tok = gw; tok < NTOK; tok += NGW) { f32x4 v[4]; float s = 0.f;
.LBB0_352:
	s_nop 0
	v_readlane_b32 s0, v249, 50
	v_readlane_b32 s1, v249, 51
	s_and_b64 vcc, exec, s[0:1]
	s_cbranch_vccz .LBB0_373
	s_cmpk_gt_i32 s16, 0x7fff
	s_cbranch_scc1 .LBB0_372
	v_readlane_b32 s0, v249, 25
	v_readlane_b32 s20, v249, 27
	v_lshlrev_b32_e32 v34, 4, v248
	v_readlane_b32 s1, v249, 26
	v_readlane_b32 s21, v249, 28
	s_waitcnt lgkmcnt(0)
	s_nop 2
	global_load_dwordx4 v[0:3], v34, s[0:1]
	global_load_dwordx4 v[4:7], v34, s[0:1] offset:1024
	global_load_dwordx4 v[8:11], v34, s[20:21]
	global_load_dwordx4 v[12:15], v34, s[20:21] offset:1024
	global_load_dwordx4 v[16:19], v34, s[0:1] offset:2048
	global_load_dwordx4 v[20:23], v34, s[0:1] offset:3072
	global_load_dwordx4 v[24:27], v34, s[20:21] offset:2048
	global_load_dwordx4 v[28:31], v34, s[20:21] offset:3072
	v_readlane_b32 s0, v249, 52
	s_lshl_b32 s0, s0, 2
	v_readlane_b32 s1, v253, 50
	s_add_i32 s20, s1, s0
	v_readlane_b32 s0, v249, 49
	s_ashr_i32 s17, s16, 31
	s_lshl_b32 s12, s0, 5
	s_lshl_b64 s[0:1], s[16:17], 11
	v_readlane_b32 s22, v251, 48
	v_lshlrev_b32_e32 v32, 2, v248
	v_readlane_b32 s23, v251, 49
	s_add_u32 s0, s22, s0
	v_or_b32_e32 v36, 0x100, v32
	s_waitcnt vmcnt(0)
	v_or_b32_e32 v46, 0x200, v32
	v_or_b32_e32 v48, 0x300, v32
	v_lshlrev_b32_e32 v32, 3, v248
	s_addc_u32 s1, s23, s1
	s_ashr_i32 s15, s14, 31
	v_lshl_add_u64 v[42:43], s[0:1], 0, v[32:33]
	s_lshl_b64 s[22:23], s[14:15], 11
	s_lshl_b64 s[0:1], s[16:17], 12
	v_readlane_b32 s17, v253, 51
	s_add_u32 s0, s17, s0
	v_readlane_b32 s17, v253, 52
	v_mov_b32_e32 v35, v33
	s_addc_u32 s1, s17, s1
	v_lshl_add_u64 v[40:41], s[96:97], 0, v[32:33]
	v_lshl_add_u64 v[44:45], s[0:1], 0, v[34:35]
	s_lshl_b64 s[26:27], s[14:15], 12
	v_lshlrev_b32_e32 v32, 1, v36
	v_lshlrev_b32_e32 v39, 1, v46
	v_lshlrev_b32_e32 v74, 1, v48
	v_lshrrev_b32_e32 v186, 1, v248
	v_lshlrev_b32_e32 v186, 4, v186
	v_and_b32_e32 v187, 1, v248
	v_lshl_add_u32 v186, v187, 9, v186
	v_lshlrev_b32_e32 v187, 3, v248
	v_sub_u32_e32 v186, v186, v187
	v_ashrrev_i32_e32 v187, 31, v186
	s_mov_b32 s100, 0xaaaaaaaa
	s_mov_b32 s101, 0xaaaaaaaa
	s_branch .LBB0_356

; __device__ __forceinline__ float bflo(unsigned u) { return __uint_as_float(u << 16); }
; __device__ __forceinline__ float bfhi(unsigned u) { return __uint_as_float(u & 0xffff0000u); }
; __device__ __forceinline__ void run_phase(const Args& a, const int ph, LAS unsigned char* lds, const int tid, const int rpt) {
;     ...
;                 for (int tok = gw; tok < NTOK; tok += NGW) { f32x4 v[4]; float s = 0.f;
; #pragma unroll
;                     for (int j = 0; j < 4; ++j) { const int co = 4 * (64 * j + lane); const u32x2 xr = *(const u32x2*)(x1r + (size_t)tok * 1024 + co); f32x4 x = (f32x4){bflo(xr.x), bfhi(xr.x), bflo(xr.y), bfhi(xr.y)} * DN_ALPHA;
; #pragma unroll
;                         for (int k = 0; k < 4; ++k) { const u32x2 w = *(const u32x2*)(yb + (size_t)(tok * 4 + k) * 1024 + co); x[0] += bflo(w.x); x[1] += bfhi(w.x); x[2] += bflo(w.y); x[3] += bfhi(w.y); }
;                         v[j] = x; s += (x[0] + x[1]) + (x[2] + x[3]); }
.LBB0_356:
	s_lshl_b32 s98, s20, 11
	s_mov_b32 s99, 0
	v_lshl_add_u64 v[190:191], v[42:43], 0, v[186:187]
	v_lshl_add_u64 v[188:189], v[40:41], 0, v[186:187]
	v_lshl_add_u64 v[182:183], v[188:189], 0, s[98:99]
	global_load_dwordx4 v[92:95], v[190:191], off
	global_load_dwordx4 v[96:99], v[190:191], off offset:1024
	global_load_dwordx4 v[100:103], v[182:183], off
	global_load_dwordx4 v[104:107], v[182:183], off offset:1024
	s_add_i32 s98, s98, 0x800
	v_lshl_add_u64 v[182:183], v[188:189], 0, s[98:99]
	global_load_dwordx4 v[108:111], v[182:183], off
	global_load_dwordx4 v[112:115], v[182:183], off offset:1024
	s_add_i32 s98, s98, 0x800
	v_lshl_add_u64 v[182:183], v[188:189], 0, s[98:99]
	global_load_dwordx4 v[116:119], v[182:183], off
	global_load_dwordx4 v[120:123], v[182:183], off offset:1024
	s_add_i32 s98, s98, 0x800
	v_lshl_add_u64 v[182:183], v[188:189], 0, s[98:99]
	global_load_dwordx4 v[124:127], v[182:183], off
	global_load_dwordx4 v[128:131], v[182:183], off offset:1024
	s_waitcnt vmcnt(0)
	v_mov_b32_dpp v192, v92 quad_perm:[1,0,3,2] row_mask:0xf bank_mask:0xf
	v_mov_b32_dpp v193, v93 quad_perm:[1,0,3,2] row_mask:0xf bank_mask:0xf
	v_mov_b32_dpp v194, v94 quad_perm:[1,0,3,2] row_mask:0xf bank_mask:0xf
	v_mov_b32_dpp v195, v95 quad_perm:[1,0,3,2] row_mask:0xf bank_mask:0xf
	v_cndmask_b32_e64 v132, v92, v194, s[100:101]
	v_cndmask_b32_e64 v133, v93, v195, s[100:101]
	v_cndmask_b32_e64 v134, v192, v94, s[100:101]
	v_cndmask_b32_e64 v135, v193, v95, s[100:101]
	v_mov_b32_dpp v192, v96 quad_perm:[1,0,3,2] row_mask:0xf bank_mask:0xf
	v_mov_b32_dpp v193, v97 quad_perm:[1,0,3,2] row_mask:0xf bank_mask:0xf
	v_mov_b32_dpp v194, v98 quad_perm:[1,0,3,2] row_mask:0xf bank_mask:0xf
	v_mov_b32_dpp v195, v99 quad_perm:[1,0,3,2] row_mask:0xf bank_mask:0xf
	v_cndmask_b32_e64 v136, v96, v194, s[100:101]
	v_cndmask_b32_e64 v137, v97, v195, s[100:101]
	v_cndmask_b32_e64 v138, v192, v98, s[100:101]
	v_cndmask_b32_e64 v139, v193, v99, s[100:101]
	v_mov_b32_dpp v192, v100 quad_perm:[1,0,3,2] row_mask:0xf bank_mask:0xf
	v_mov_b32_dpp v193, v101 quad_perm:[1,0,3,2] row_mask:0xf bank_mask:0xf
	v_mov_b32_dpp v194, v102 quad_perm:[1,0,3,2] row_mask:0xf bank_mask:0xf
	v_mov_b32_dpp v195, v103 quad_perm:[1,0,3,2] row_mask:0xf bank_mask:0xf
	v_cndmask_b32_e64 v140, v100, v194, s[100:101]
	v_cndmask_b32_e64 v141, v101, v195, s[100:101]
	v_cndmask_b32_e64 v148, v192, v102, s[100:101]
	v_cndmask_b32_e64 v149, v193, v103, s[100:101]
	v_mov_b32_dpp v192, v104 quad_perm:[1,0,3,2] row_mask:0xf bank_mask:0xf
	v_mov_b32_dpp v193, v105 quad_perm:[1,0,3,2] row_mask:0xf bank_mask:0xf
	v_mov_b32_dpp v194, v106 quad_perm:[1,0,3,2] row_mask:0xf bank_mask:0xf
	v_mov_b32_dpp v195, v107 quad_perm:[1,0,3,2] row_mask:0xf bank_mask:0xf
	v_cndmask_b32_e64 v156, v104, v194, s[100:101]
	v_cndmask_b32_e64 v157, v105, v195, s[100:101]
	v_cndmask_b32_e64 v164, v192, v106, s[100:101]
	v_cndmask_b32_e64 v165, v193, v107, s[100:101]
	v_mov_b32_dpp v192, v108 quad_perm:[1,0,3,2] row_mask:0xf bank_mask:0xf
	v_mov_b32_dpp v193, v109 quad_perm:[1,0,3,2] row_mask:0xf bank_mask:0xf
	v_mov_b32_dpp v194, v110 quad_perm:[1,0,3,2] row_mask:0xf bank_mask:0xf
	v_mov_b32_dpp v195, v111 quad_perm:[1,0,3,2] row_mask:0xf bank_mask:0xf
	v_cndmask_b32_e64 v142, v108, v194, s[100:101]
	v_cndmask_b32_e64 v143, v109, v195, s[100:101]
	v_cndmask_b32_e64 v150, v192, v110, s[100:101]
	v_cndmask_b32_e64 v151, v193, v111, s[100:101]
	v_mov_b32_dpp v192, v112 quad_perm:[1,0,3,2] row_mask:0xf bank_mask:0xf
	v_mov_b32_dpp v193, v113 quad_perm:[1,0,3,2] row_mask:0xf bank_mask:0xf
	v_mov_b32_dpp v194, v114 quad_perm:[1,0,3,2] row_mask:0xf bank_mask:0xf
	v_mov_b32_dpp v195, v115 quad_perm:[1,0,3,2] row_mask:0xf bank_mask:0xf
	v_cndmask_b32_e64 v158, v112, v194, s[100:101]
	v_cndmask_b32_e64 v159, v113, v195, s[100:101]
	v_cndmask_b32_e64 v176, v192, v114, s[100:101]
	v_cndmask_b32_e64 v177, v193, v115, s[100:101]
	v_mov_b32_dpp v192, v116 quad_perm:[1,0,3,2] row_mask:0xf bank_mask:0xf
	v_mov_b32_dpp v193, v117 quad_perm:[1,0,3,2] row_mask:0xf bank_mask:0xf
	v_mov_b32_dpp v194, v118 quad_perm:[1,0,3,2] row_mask:0xf bank_mask:0xf
	v_mov_b32_dpp v195, v119 quad_perm:[1,0,3,2] row_mask:0xf bank_mask:0xf
	v_cndmask_b32_e64 v144, v116, v194, s[100:101]
	v_cndmask_b32_e64 v145, v117, v195, s[100:101]
	v_cndmask_b32_e64 v152, v192, v118, s[100:101]
	v_cndmask_b32_e64 v153, v193, v119, s[100:101]
	v_mov_b32_dpp v192, v120 quad_perm:[1,0,3,2] row_mask:0xf bank_mask:0xf
	v_mov_b32_dpp v193, v121 quad_perm:[1,0,3,2] row_mask:0xf bank_mask:0xf
	v_mov_b32_dpp v194, v122 quad_perm:[1,0,3,2] row_mask:0xf bank_mask:0xf
	v_mov_b32_dpp v195, v123 quad_perm:[1,0,3,2] row_mask:0xf bank_mask:0xf
	v_cndmask_b32_e64 v160, v120, v194, s[100:101]
	v_cndmask_b32_e64 v161, v121, v195, s[100:101]
	v_cndmask_b32_e64 v178, v192, v122, s[100:101]
	v_cndmask_b32_e64 v179, v193, v123, s[100:101]
	v_mov_b32_dpp v192, v124 quad_perm:[1,0,3,2] row_mask:0xf bank_mask:0xf
	v_mov_b32_dpp v193, v125 quad_perm:[1,0,3,2] row_mask:0xf bank_mask:0xf
	v_mov_b32_dpp v194, v126 quad_perm:[1,0,3,2] row_mask:0xf bank_mask:0xf
	v_mov_b32_dpp v195, v127 quad_perm:[1,0,3,2] row_mask:0xf bank_mask:0xf
	v_cndmask_b32_e64 v146, v124, v194, s[100:101]
	v_cndmask_b32_e64 v147, v125, v195, s[100:101]
	v_cndmask_b32_e64 v154, v192, v126, s[100:101]
	v_cndmask_b32_e64 v155, v193, v127, s[100:101]
	v_mov_b32_dpp v192, v128 quad_perm:[1,0,3,2] row_mask:0xf bank_mask:0xf
	v_mov_b32_dpp v193, v129 quad_perm:[1,0,3,2] row_mask:0xf bank_mask:0xf
	v_mov_b32_dpp v194, v130 quad_perm:[1,0,3,2] row_mask:0xf bank_mask:0xf
	v_mov_b32_dpp v195, v131 quad_perm:[1,0,3,2] row_mask:0xf bank_mask:0xf
; __device__ __forceinline__ float bflo(unsigned u) { return __uint_as_float(u << 16); }
; __device__ __forceinline__ float bfhi(unsigned u) { return __uint_as_float(u & 0xffff0000u); }
; __device__ __forceinline__ void run_phase(const Args& a, const int ph, LAS unsigned char* lds, const int tid, const int rpt) {
;     ...
;                 for (int tok = gw; tok < NTOK; tok += NGW) { f32x4 v[4]; float s = 0.f;
; #pragma unroll
;                     for (int j = 0; j < 4; ++j) { const int co = 4 * (64 * j + lane); const u32x2 xr = *(const u32x2*)(x1r + (size_t)tok * 1024 + co); f32x4 x = (f32x4){bflo(xr.x), bfhi(xr.x), bflo(xr.y), bfhi(xr.y)} * DN_ALPHA;
; #pragma unroll
;                         for (int k = 0; k < 4; ++k) { const u32x2 w = *(const u32x2*)(yb + (size_t)(tok * 4 + k) * 1024 + co); x[0] += bflo(w.x); x[1] += bfhi(w.x); x[2] += bflo(w.y); x[3] += bfhi(w.y); }
;                         v[j] = x; s += (x[0] + x[1]) + (x[2] + x[3]); }
;                     const float mean = wave_sum(s, lane) * (1.f / 1024.f); float s2 = 0.f;
	v_cndmask_b32_e64 v162, v128, v194, s[100:101]
	v_cndmask_b32_e64 v163, v129, v195, s[100:101]
	v_cndmask_b32_e64 v180, v192, v130, s[100:101]
	v_cndmask_b32_e64 v181, v193, v131, s[100:101]
	v_mov_b32_e32 v34, v132
	v_mov_b32_e32 v35, v133
	s_mov_b32 s44, 0x3fb504f3
	v_lshlrev_b32_e32 v36, 16, v34
	v_and_b32_e32 v37, 0xffff0000, v34
	v_lshlrev_b32_e32 v46, 16, v35
	v_and_b32_e32 v47, 0xffff0000, v35
	v_mov_b32_e32 v48, v140
	v_mov_b32_e32 v49, v141
	v_mov_b32_e32 v50, v142
	v_mov_b32_e32 v51, v143
	v_mov_b32_e32 v52, v144
	v_mov_b32_e32 v53, v145
	v_mov_b32_e32 v54, v146
	v_mov_b32_e32 v55, v147
	v_mov_b32_e32 v56, v150
	v_mov_b32_e32 v57, v151
	v_mov_b32_e32 v58, v152
	v_mov_b32_e32 v59, v153
	v_mov_b32_e32 v60, v154
	v_mov_b32_e32 v61, v155
	v_lshlrev_b32_e32 v34, 16, v48
	v_and_b32_e32 v35, 0xffff0000, v48
	v_pk_fma_f32 v[34:35], v[36:37], s[44:45], v[34:35] op_sel_hi:[1,0,1]
	v_lshlrev_b32_e32 v36, 16, v50
	v_and_b32_e32 v37, 0xffff0000, v50
	v_pk_add_f32 v[34:35], v[34:35], v[36:37]
	v_lshlrev_b32_e32 v36, 16, v52
	v_and_b32_e32 v37, 0xffff0000, v52
	v_pk_add_f32 v[34:35], v[34:35], v[36:37]
	v_lshlrev_b32_e32 v36, 16, v54
	v_and_b32_e32 v37, 0xffff0000, v54
	v_pk_add_f32 v[34:35], v[34:35], v[36:37]
	v_lshlrev_b32_e32 v36, 16, v49
	v_and_b32_e32 v37, 0xffff0000, v49
	v_pk_fma_f32 v[36:37], v[46:47], s[44:45], v[36:37] op_sel_hi:[1,0,1]
	v_lshlrev_b32_e32 v46, 16, v51
	v_and_b32_e32 v47, 0xffff0000, v51
	v_pk_add_f32 v[36:37], v[36:37], v[46:47]
	v_lshlrev_b32_e32 v46, 16, v53
	v_and_b32_e32 v47, 0xffff0000, v53
	v_pk_add_f32 v[36:37], v[36:37], v[46:47]
	v_lshlrev_b32_e32 v46, 16, v55
	v_and_b32_e32 v47, 0xffff0000, v55
	v_pk_add_f32 v[36:37], v[36:37], v[46:47]
	v_mov_b32_e32 v46, v34
	v_mov_b32_e32 v47, v36
	v_mov_b32_e32 v48, v35
	v_mov_b32_e32 v49, v37
	v_pk_add_f32 v[46:47], v[46:47], v[48:49]
	v_mov_b32_e32 v48, v134
	v_mov_b32_e32 v49, v135
	v_mov_b32_e32 v54, v148
	v_mov_b32_e32 v55, v149
	v_add_f32_e32 v46, v46, v47
	v_add_f32_e32 v46, 0, v46
	v_lshlrev_b32_e32 v50, 16, v48
	v_and_b32_e32 v51, 0xffff0000, v48
	v_lshlrev_b32_e32 v52, 16, v49
	v_and_b32_e32 v53, 0xffff0000, v49
	v_lshlrev_b32_e32 v48, 16, v54
	v_and_b32_e32 v49, 0xffff0000, v54
	v_pk_fma_f32 v[48:49], v[50:51], s[44:45], v[48:49] op_sel_hi:[1,0,1]
	v_lshlrev_b32_e32 v50, 16, v56
	v_and_b32_e32 v51, 0xffff0000, v56
	v_pk_add_f32 v[48:49], v[48:49], v[50:51]
	v_lshlrev_b32_e32 v50, 16, v58
	v_and_b32_e32 v51, 0xffff0000, v58
	v_pk_add_f32 v[48:49], v[48:49], v[50:51]
	v_lshlrev_b32_e32 v50, 16, v60
	v_and_b32_e32 v51, 0xffff0000, v60
	v_pk_add_f32 v[48:49], v[48:49], v[50:51]
	v_lshlrev_b32_e32 v50, 16, v55
	v_and_b32_e32 v51, 0xffff0000, v55
	v_pk_fma_f32 v[50:51], v[52:53], s[44:45], v[50:51] op_sel_hi:[1,0,1]
	v_lshlrev_b32_e32 v52, 16, v57
	v_and_b32_e32 v53, 0xffff0000, v57
	v_pk_add_f32 v[50:51], v[50:51], v[52:53]
	v_lshlrev_b32_e32 v52, 16, v59
	v_and_b32_e32 v53, 0xffff0000, v59
	v_pk_add_f32 v[50:51], v[50:51], v[52:53]
	v_lshlrev_b32_e32 v52, 16, v61
	v_and_b32_e32 v53, 0xffff0000, v61
	v_pk_add_f32 v[50:51], v[50:51], v[52:53]
	v_mov_b32_e32 v52, v48
	v_mov_b32_e32 v53, v50
	v_mov_b32_e32 v54, v49
	v_mov_b32_e32 v55, v51
	v_pk_add_f32 v[52:53], v[52:53], v[54:55]
	s_nop 0
	v_pk_add_f32 v[56:57], v[52:53], v[52:53] op_sel:[0,1] op_sel_hi:[1,0]
	v_mov_b32_e32 v52, v136
	v_mov_b32_e32 v53, v137
	v_mov_b32_e32 v60, v156
	v_mov_b32_e32 v61, v157
	v_mov_b32_e32 v62, v158
	v_mov_b32_e32 v63, v159
	v_mov_b32_e32 v64, v160
	v_mov_b32_e32 v65, v161
	v_mov_b32_e32 v66, v162
	v_mov_b32_e32 v67, v163
	v_lshlrev_b32_e32 v54, 16, v52
	v_and_b32_e32 v55, 0xffff0000, v52
	v_lshlrev_b32_e32 v58, 16, v53
	v_and_b32_e32 v59, 0xffff0000, v53
	v_lshlrev_b32_e32 v52, 16, v60
	v_and_b32_e32 v53, 0xffff0000, v60
	v_pk_fma_f32 v[52:53], v[54:55], s[44:45], v[52:53] op_sel_hi:[1,0,1]
	v_lshlrev_b32_e32 v54, 16, v62
	v_and_b32_e32 v55, 0xffff0000, v62
	v_pk_add_f32 v[52:53], v[52:53], v[54:55]
	v_lshlrev_b32_e32 v54, 16, v64
	v_and_b32_e32 v55, 0xffff0000, v64
	v_pk_add_f32 v[52:53], v[52:53], v[54:55]
	v_lshlrev_b32_e32 v54, 16, v66
	v_and_b32_e32 v55, 0xffff0000, v66
	v_pk_add_f32 v[52:53], v[52:53], v[54:55]
	v_lshlrev_b32_e32 v54, 16, v61
	v_and_b32_e32 v55, 0xffff0000, v61
	v_pk_fma_f32 v[54:55], v[58:59], s[44:45], v[54:55] op_sel_hi:[1,0,1]
	v_lshlrev_b32_e32 v58, 16, v63
	v_and_b32_e32 v59, 0xffff0000, v63
	v_mov_b32_e32 v62, v138
	v_mov_b32_e32 v63, v139
	v_pk_add_f32 v[54:55], v[54:55], v[58:59]
	v_lshlrev_b32_e32 v58, 16, v65
	v_and_b32_e32 v59, 0xffff0000, v65
	v_pk_add_f32 v[54:55], v[54:55], v[58:59]
	v_lshlrev_b32_e32 v58, 16, v67
	v_and_b32_e32 v59, 0xffff0000, v67
	v_mov_b32_e32 v72, v164
	v_mov_b32_e32 v73, v165
	v_mov_b32_e32 v70, v176
	v_mov_b32_e32 v71, v177
	v_mov_b32_e32 v68, v178
	v_mov_b32_e32 v69, v179
	v_mov_b32_e32 v66, v180
	v_mov_b32_e32 v67, v181
	v_pk_add_f32 v[54:55], v[54:55], v[58:59]
	v_pk_add_f32 v[58:59], v[52:53], v[52:53] op_sel:[0,1] op_sel_hi:[1,0]
	v_pk_add_f32 v[60:61], v[54:55], v[54:55] op_sel:[0,1] op_sel_hi:[1,0]
	v_readlane_b32 s36, v249, 29
	v_readlane_b32 s37, v249, 30
; __device__ __forceinline__ unsigned pk2(float lo, float hi) { unsigned r; asm("v_cvt_pk_bf16_f32 %0, %1, %2" : "=v"(r) : "v"(lo), "v"(hi)); return r; }
; __device__ __forceinline__ void run_phase(const Args& a, const int ph, LAS unsigned char* lds, const int tid, const int rpt) {
;     ...
;                     const float mean = wave_sum(s, lane) * (1.f / 1024.f); float s2 = 0.f;
; #pragma unroll
;                     for (int j = 0; j < 4; ++j) { v[j] = v[j] - mean; s2 += (v[j][0] * v[j][0] + v[j][1] * v[j][1]) + (v[j][2] * v[j][2] + v[j][3] * v[j][3]); }
;                     const float rstd = rsqrtf(wave_sum(s2, lane) * (1.f / 1024.f) + LN_EPS);
; #pragma unroll
;                     for (int j = 0; j < 4; ++j) { const int co = 4 * (64 * j + lane); const f32x4 y = v[j] * rstd * gv[j] + bv[j];
;                         if (l + 1 == DEPTH) *(f32x4*)(a.out + (size_t)tok * 1024 + co) = y;
;                         else { u32x2 w; w.x = pk2(y[0], y[1]); w.y = pk2(y[2], y[3]); *(u32x2*)(xb + (size_t)tok * 1024 + co) = w; } } }
	v_lshlrev_b32_e32 v64, 16, v62
	v_and_b32_e32 v65, 0xffff0000, v62
	v_lshlrev_b32_e32 v62, 16, v63
	v_and_b32_e32 v63, 0xffff0000, v63
	v_lshlrev_b32_e32 v76, 16, v72
	v_and_b32_e32 v77, 0xffff0000, v72
	v_lshlrev_b32_e32 v72, 16, v73
	v_and_b32_e32 v73, 0xffff0000, v73
	v_pk_fma_f32 v[64:65], v[64:65], s[44:45], v[76:77] op_sel_hi:[1,0,1]
	v_lshlrev_b32_e32 v76, 16, v70
	v_and_b32_e32 v77, 0xffff0000, v70
	v_pk_fma_f32 v[62:63], v[62:63], s[44:45], v[72:73] op_sel_hi:[1,0,1]
	v_lshlrev_b32_e32 v70, 16, v71
	v_and_b32_e32 v71, 0xffff0000, v71
	v_pk_add_f32 v[64:65], v[64:65], v[76:77]
	v_lshlrev_b32_e32 v76, 16, v68
	v_and_b32_e32 v77, 0xffff0000, v68
	v_pk_add_f32 v[62:63], v[62:63], v[70:71]
	v_lshlrev_b32_e32 v68, 16, v69
	v_and_b32_e32 v69, 0xffff0000, v69
	v_pk_add_f32 v[64:65], v[64:65], v[76:77]
	v_lshlrev_b32_e32 v76, 16, v66
	v_and_b32_e32 v77, 0xffff0000, v66
	v_pk_add_f32 v[62:63], v[62:63], v[68:69]
	v_lshlrev_b32_e32 v66, 16, v67
	v_and_b32_e32 v67, 0xffff0000, v67
	v_pk_add_f32 v[64:65], v[64:65], v[76:77]
	v_pk_add_f32 v[62:63], v[62:63], v[66:67]
	v_mov_b32_e32 v47, v64
	v_mov_b32_e32 v57, v65
	v_mov_b32_e32 v59, v62
	v_mov_b32_e32 v61, v63
	v_pk_add_f32 v[46:47], v[46:47], v[56:57]
	v_pk_add_f32 v[56:57], v[58:59], v[60:61]
	s_nop 0
	v_pk_add_f32 v[46:47], v[46:47], v[56:57]
	s_nop 0
	v_add_f32_e32 v46, v46, v47
	v_mov_b32_e32 v47, v33
	s_nop 0
	v_add_f32_dpp v46, v46, v46 quad_perm:[1,0,3,2] row_mask:0xf bank_mask:0xf bound_ctrl:1
	s_nop 1
	v_add_f32_dpp v46, v46, v46 quad_perm:[2,3,0,1] row_mask:0xf bank_mask:0xf bound_ctrl:1
	s_nop 1
	v_add_f32_dpp v46, v46, v46 row_half_mirror row_mask:0xf bank_mask:0xf bound_ctrl:1
	s_nop 1
	v_add_f32_dpp v46, v46, v46 row_mirror row_mask:0xf bank_mask:0xf bound_ctrl:1
	s_nop 1
	v_mov_b32_dpp v47, v46 row_bcast:15 row_mask:0xa bank_mask:0xf
	v_add_f32_e32 v46, v46, v47
	v_mov_b32_e32 v47, v33
	s_nop 1
	v_mov_b32_dpp v47, v46 row_bcast:31 row_mask:0xc bank_mask:0xf
	v_add_f32_e32 v46, v46, v47
	s_nop 0
	v_readlane_b32 s0, v46, 63
	s_nop 1
	v_fma_f32 v35, s0, v210, v35
	v_fmac_f32_e32 v34, s0, v210
	v_fma_f32 v37, s0, v210, v37
	v_fmac_f32_e32 v36, s0, v210
	v_pk_mul_f32 v[46:47], v[36:37], v[36:37]
	v_pk_mul_f32 v[56:57], v[34:35], v[34:35]
	v_fma_f32 v51, s0, v210, v51
	v_pk_mov_b32 v[58:59], v[56:57], v[46:47] op_sel:[1,0]
	v_mov_b32_e32 v57, v47
	v_fmac_f32_e32 v50, s0, v210
	v_fma_f32 v49, s0, v210, v49
	v_fmac_f32_e32 v48, s0, v210
	v_pk_add_f32 v[46:47], v[58:59], v[56:57]
	v_pk_mul_f32 v[56:57], v[50:51], v[50:51]
	v_pk_mul_f32 v[58:59], v[48:49], v[48:49]
	v_fma_f32 v53, s0, v210, v53
	v_pk_mov_b32 v[60:61], v[58:59], v[56:57] op_sel:[1,0]
	v_mov_b32_e32 v59, v57
	v_pk_add_f32 v[56:57], v[60:61], v[58:59]
	v_fmac_f32_e32 v52, s0, v210
	v_fmac_f32_e32 v64, s0, v210
	v_mul_f32_e32 v58, v53, v53
	v_fma_f32 v55, s0, v210, v55
	v_mul_f32_e32 v60, v64, v64
	v_pk_fma_f32 v[58:59], v[52:53], v[52:53], v[58:59] op_sel_hi:[1,1,0]
	v_fmac_f32_e32 v54, s0, v210
	v_fma_f32 v63, s0, v210, v63
	v_fmac_f32_e32 v62, s0, v210
	v_fma_f32 v65, s0, v210, v65
	v_mov_b32_e32 v59, v60
	v_mul_f32_e32 v60, v55, v55
	v_mul_f32_e32 v66, v65, v65
	v_mul_f32_e32 v67, v62, v62
	v_mul_f32_e32 v68, v63, v63
	v_pk_fma_f32 v[60:61], v[54:55], v[54:55], v[60:61] op_sel_hi:[1,1,0]
	v_pk_add_f32 v[46:47], v[46:47], v[46:47] op_sel:[0,1] op_sel_hi:[1,0]
	v_pk_add_f32 v[56:57], v[56:57], v[56:57] op_sel:[0,1] op_sel_hi:[1,0]
	v_mov_b32_e32 v61, v66
	v_mov_b32_e32 v47, v67
	v_mov_b32_e32 v57, v68
	v_pk_add_f32 v[58:59], v[58:59], v[60:61]
	v_pk_add_f32 v[46:47], v[46:47], v[56:57]
	s_nop 0
	v_pk_add_f32 v[46:47], v[58:59], v[46:47]
	s_nop 0
	v_add_f32_e32 v46, v46, v47
	v_mov_b32_e32 v47, v33
	s_nop 0
	v_add_f32_dpp v46, v46, v46 quad_perm:[1,0,3,2] row_mask:0xf bank_mask:0xf bound_ctrl:1
	s_nop 1
	v_add_f32_dpp v46, v46, v46 quad_perm:[2,3,0,1] row_mask:0xf bank_mask:0xf bound_ctrl:1
	s_nop 1
	v_add_f32_dpp v46, v46, v46 row_half_mirror row_mask:0xf bank_mask:0xf bound_ctrl:1
	s_nop 1
	v_add_f32_dpp v46, v46, v46 row_mirror row_mask:0xf bank_mask:0xf bound_ctrl:1
	s_nop 1
	v_mov_b32_dpp v47, v46 row_bcast:15 row_mask:0xa bank_mask:0xf
	v_add_f32_e32 v46, v46, v47
	v_mov_b32_e32 v47, v33
	s_nop 1
	v_mov_b32_dpp v47, v46 row_bcast:31 row_mask:0xc bank_mask:0xf
	v_add_f32_e32 v46, v46, v47
	s_nop 0
	v_readlane_b32 s0, v46, 63
	s_nop 1
	v_fma_f32 v46, s0, v247, v206
	v_cmp_gt_f32_e32 vcc, s33, v46
	v_mul_f32_e32 v47, 0x4b800000, v46
	s_mov_b64 s[0:1], -1
	v_cndmask_b32_e32 v46, v46, v47, vcc
	v_rsq_f32_e32 v46, v46
	s_nop 0
	v_mul_f32_e32 v47, 0x45800000, v46
	v_cndmask_b32_e32 v46, v46, v47, vcc
	v_pk_mul_f32 v[34:35], v[34:35], v[46:47] op_sel_hi:[1,0]
	v_pk_mul_f32 v[36:37], v[36:37], v[46:47] op_sel_hi:[1,0]
	v_pk_fma_f32 v[34:35], v[0:1], v[34:35], v[8:9]
	v_pk_fma_f32 v[36:37], v[2:3], v[36:37], v[10:11]
	s_and_b64 vcc, exec, s[36:37]
	s_cbranch_vccz .LBB0_358
	v_add_co_u32_e32 v58, vcc, 0xe1000000, v42
	v_cvt_pk_bf16_f32 v56, v34, v35
	v_cvt_pk_bf16_f32 v57, v36, v37
	s_mov_b64 s[0:1], 0
	s_nop 0
	v_addc_co_u32_e32 v59, vcc, -1, v43, vcc
	global_store_dwordx2 v[58:59], v[56:57], off
